# v4: attention main loop K/V tile loads hoisted to the top of each half into fresh staging registers (more flight time before the LDS staging wait)
# speedup vs baseline: 1.0099x; 1.0015x over previous
.LBB0_2414:
	v_lshl_add_u64 v[228:229], s[38:39], 0, v[162:163]
	v_lshl_add_u64 v[230:231], s[38:39], 0, v[160:161]
	v_lshl_add_u64 v[232:233], s[38:39], 0, v[158:159]
	s_mov_b64 s[100:101], 0x2a108000
	v_lshl_add_u64 v[212:213], v[228:229], 0, s[100:101]
	s_mov_b64 s[100:101], 0x2a10a000
	v_lshl_add_u64 v[216:217], v[228:229], 0, s[100:101]
	s_mov_b64 s[100:101], 0x1e106000
	v_lshl_add_u64 v[220:221], v[230:231], 0, s[100:101]
	v_lshl_add_u64 v[224:225], v[232:233], 0, s[100:101]
	global_load_dwordx4 v[212:215], v[212:213], off
	global_load_dwordx4 v[216:219], v[216:217], off
	global_load_dwordx4 v[220:223], v[220:221], off
	s_and_saveexec_b64 s[14:15], s[12:13]
	s_cbranch_execz .Lattn_ldA_skip
	global_load_dwordx4 v[224:227], v[224:225], off
.Lattn_ldA_skip:
	s_or_b64 exec, exec, s[14:15]
	s_nop 1
	ds_read_b128 v[188:191], v181 offset:12288
	ds_read_b128 v[196:199], v181 offset:18432
	ds_read_b128 v[192:195], v182 offset:12288
	ds_read_b128 v[200:203], v182 offset:18432
	v_add_f32_e32 v2, 0, v150
	v_mov_b64_e32 v[82:83], s[30:31]
	v_add_f32_e32 v2, v151, v2
	v_mov_b64_e32 v[80:81], s[28:29]
	v_mov_b64_e32 v[78:79], s[26:27]
	v_mov_b64_e32 v[76:77], s[24:25]
	v_mov_b64_e32 v[74:75], s[22:23]
	v_mov_b64_e32 v[72:73], s[20:21]
	v_mov_b64_e32 v[70:71], s[18:19]
	v_mov_b64_e32 v[68:69], s[16:17]
	v_mov_b64_e32 v[98:99], v[82:83]
	v_add_f32_e32 v2, v152, v2
	v_mov_b64_e32 v[96:97], v[80:81]
	v_mov_b64_e32 v[94:95], v[78:79]
	v_mov_b64_e32 v[92:93], v[76:77]
	v_mov_b64_e32 v[90:91], v[74:75]
	v_mov_b64_e32 v[88:89], v[72:73]
	v_mov_b64_e32 v[86:87], v[70:71]
	v_mov_b64_e32 v[84:85], v[68:69]
	v_add_f32_e32 v2, v153, v2
	s_waitcnt lgkmcnt(1)
	v_mfma_scale_f32_32x32x64_f8f6f4 v[84:99], v[188:195], v[116:123], v[84:99], v170, v170 op_sel_hi:[0,0,0]
	s_waitcnt lgkmcnt(0)
	v_mfma_scale_f32_32x32x64_f8f6f4 v[68:83], v[196:203], v[116:123], v[68:83], v170, v170 op_sel_hi:[0,0,0]
	ds_read_b128 v[188:191], v181 offset:12352
	ds_read_b128 v[196:199], v181 offset:18496
	ds_read_b128 v[192:195], v182 offset:12352
	ds_read_b128 v[200:203], v182 offset:18496
	v_add_f32_e32 v2, v154, v2
	v_add_f32_e32 v2, v165, v2
	v_add_f32_e32 v2, v166, v2
	v_add_f32_e32 v2, v168, v2
	v_add_f32_e32 v2, v145, v2
	s_waitcnt lgkmcnt(1)
	v_mfma_scale_f32_32x32x64_f8f6f4 v[84:99], v[188:195], v[108:115], v[84:99], v170, v170 op_sel_hi:[0,0,0]
	s_waitcnt lgkmcnt(0)
	v_mfma_scale_f32_32x32x64_f8f6f4 v[68:83], v[196:203], v[108:115], v[68:83], v170, v170 op_sel_hi:[0,0,0]
	ds_read_b128 v[188:191], v181 offset:12416
	ds_read_b128 v[196:199], v181 offset:18560
	ds_read_b128 v[192:195], v182 offset:12416
	ds_read_b128 v[200:203], v182 offset:18560
	v_add_f32_e32 v2, v146, v2
	v_add_f32_e32 v2, v147, v2
	v_add_f32_e32 v2, v148, v2
	v_exp_f32_e32 v169, v140
	v_add_f32_e32 v2, v149, v2
	s_waitcnt lgkmcnt(1)
	v_mfma_scale_f32_32x32x64_f8f6f4 v[84:99], v[188:195], v[100:107], v[84:99], v170, v170 op_sel_hi:[0,0,0]
	v_exp_f32_e32 v188, v141
	v_add_f32_e32 v2, v155, v2
	v_exp_f32_e32 v136, v136
	v_add_f32_e32 v2, v164, v2
	v_exp_f32_e32 v137, v137
	v_add_f32_e32 v2, v167, v2
	v_exp_f32_e32 v134, v134
	v_add_f32_e32 v2, v169, v2
	v_exp_f32_e32 v135, v135
	v_add_f32_e32 v2, v188, v2
	v_exp_f32_e32 v130, v130
	v_add_f32_e32 v2, v136, v2
	v_exp_f32_e32 v131, v131
	v_add_f32_e32 v2, v137, v2
	v_exp_f32_e32 v128, v128
	v_add_f32_e32 v2, v134, v2
	v_exp_f32_e32 v129, v129
	v_add_f32_e32 v2, v135, v2
	v_exp_f32_e32 v189, v142
	v_add_f32_e32 v2, v130, v2
	v_exp_f32_e32 v190, v143
	v_add_f32_e32 v2, v131, v2
	v_exp_f32_e32 v138, v138
	v_add_f32_e32 v2, v128, v2
	v_exp_f32_e32 v139, v139
	v_add_f32_e32 v2, v129, v2
	v_exp_f32_e32 v132, v132
	v_add_f32_e32 v2, v189, v2
	v_exp_f32_e32 v133, v133
	v_add_f32_e32 v2, v190, v2
	v_add_f32_e32 v2, v138, v2
	v_add_f32_e32 v2, v139, v2
	v_add_f32_e32 v2, v132, v2
	v_add_f32_e32 v2, v133, v2
	v_mov_b32_e32 v187, v2
	v_cvt_pk_bf16_f32 v140, v150, v151
	v_cvt_pk_bf16_f32 v141, v152, v153
	v_cvt_pk_bf16_f32 v142, v154, v165
	v_cvt_pk_bf16_f32 v143, v166, v168
	v_cvt_pk_bf16_f32 v144, v145, v146
	v_cvt_pk_bf16_f32 v145, v147, v148
	v_cvt_pk_bf16_f32 v146, v149, v155
	v_cvt_pk_bf16_f32 v147, v164, v167
	v_cvt_pk_bf16_f32 v148, v169, v188
	v_cvt_pk_bf16_f32 v149, v136, v137
	v_cvt_pk_bf16_f32 v150, v134, v135
	v_cvt_pk_bf16_f32 v151, v130, v131
	v_cvt_pk_bf16_f32 v152, v128, v129
	v_cvt_pk_bf16_f32 v153, v189, v190
	v_cvt_pk_bf16_f32 v154, v138, v139
	v_cvt_pk_bf16_f32 v155, v132, v133
	s_waitcnt lgkmcnt(0)
	v_mfma_scale_f32_32x32x64_f8f6f4 v[68:83], v[196:203], v[100:107], v[68:83], v170, v170 op_sel_hi:[0,0,0]
	v_permlane32_swap_b32_e32 v2, v187
	v_permlane32_swap_b32_e32 v140, v142
	v_permlane32_swap_b32_e32 v141, v143
	v_permlane32_swap_b32_e32 v144, v146
	v_permlane32_swap_b32_e32 v145, v147
	v_permlane32_swap_b32_e32 v148, v150
	v_permlane32_swap_b32_e32 v149, v151
	v_permlane32_swap_b32_e32 v152, v154
	v_permlane32_swap_b32_e32 v153, v155
	ds_read_b64_tr_b16 v[188:189], v178 offset:0
	ds_read_b64_tr_b16 v[190:191], v178 offset:0x800
	ds_read_b64_tr_b16 v[192:193], v178 offset:0x1000
	ds_read_b64_tr_b16 v[194:195], v178 offset:0x1800
	ds_read_b64_tr_b16 v[196:197], v178 offset:0x2000
	ds_read_b64_tr_b16 v[198:199], v178 offset:0x2800
	ds_read_b64_tr_b16 v[200:201], v178 offset:0x3000
	ds_read_b64_tr_b16 v[202:203], v178 offset:0x3800
	s_waitcnt lgkmcnt(0)
	s_nop 0
	v_mfma_f32_32x32x16_bf16 v[52:67], v[140:143], v[188:191], v[52:67]
	ds_read_b64_tr_b16 v[188:189], v178 offset:0x200
	ds_read_b64_tr_b16 v[190:191], v178 offset:0xa00
	v_mfma_f32_32x32x16_bf16 v[52:67], v[144:147], v[192:195], v[52:67]
	ds_read_b64_tr_b16 v[192:193], v178 offset:0x1200
	ds_read_b64_tr_b16 v[194:195], v178 offset:0x1a00
	v_mfma_f32_32x32x16_bf16 v[52:67], v[148:151], v[196:199], v[52:67]
	ds_read_b64_tr_b16 v[196:197], v178 offset:0x2200
	ds_read_b64_tr_b16 v[198:199], v178 offset:0x2a00
	v_mfma_f32_32x32x16_bf16 v[52:67], v[152:155], v[200:203], v[52:67]
	ds_read_b64_tr_b16 v[200:201], v178 offset:0x3200
	ds_read_b64_tr_b16 v[202:203], v178 offset:0x3a00
	s_waitcnt lgkmcnt(0)
	v_mfma_f32_32x32x16_bf16 v[36:51], v[140:143], v[188:191], v[36:51]
	ds_read_b64_tr_b16 v[188:189], v178 offset:0x400
	ds_read_b64_tr_b16 v[190:191], v178 offset:0xc00
	v_mfma_f32_32x32x16_bf16 v[36:51], v[144:147], v[192:195], v[36:51]
	ds_read_b64_tr_b16 v[192:193], v178 offset:0x1400
	ds_read_b64_tr_b16 v[194:195], v178 offset:0x1c00
	v_mfma_f32_32x32x16_bf16 v[36:51], v[148:151], v[196:199], v[36:51]
	ds_read_b64_tr_b16 v[196:197], v178 offset:0x2400
	ds_read_b64_tr_b16 v[198:199], v178 offset:0x2c00
	v_mfma_f32_32x32x16_bf16 v[36:51], v[152:155], v[200:203], v[36:51]
	ds_read_b64_tr_b16 v[200:201], v178 offset:0x3400
	ds_read_b64_tr_b16 v[202:203], v178 offset:0x3c00
	s_waitcnt lgkmcnt(0)
	v_mfma_f32_32x32x16_bf16 v[20:35], v[140:143], v[188:191], v[20:35]
	ds_read_b64_tr_b16 v[188:189], v178 offset:0x600
	ds_read_b64_tr_b16 v[190:191], v178 offset:0xe00
	v_mfma_f32_32x32x16_bf16 v[20:35], v[144:147], v[192:195], v[20:35]
	ds_read_b64_tr_b16 v[192:193], v178 offset:0x1600
	ds_read_b64_tr_b16 v[194:195], v178 offset:0x1e00
	v_mfma_f32_32x32x16_bf16 v[20:35], v[148:151], v[196:199], v[20:35]
	ds_read_b64_tr_b16 v[196:197], v178 offset:0x2600
	ds_read_b64_tr_b16 v[198:199], v178 offset:0x2e00
	v_mfma_f32_32x32x16_bf16 v[20:35], v[152:155], v[200:203], v[20:35]
	ds_read_b64_tr_b16 v[200:201], v178 offset:0x3600
	ds_read_b64_tr_b16 v[202:203], v178 offset:0x3e00
	s_waitcnt lgkmcnt(0)
	v_mfma_f32_32x32x16_bf16 v[4:19], v[140:143], v[188:191], v[4:19]
	v_max_f32_e32 v140, v85, v85
	v_max_f32_e32 v141, v84, v84
	v_max_f32_e32 v140, v141, v140
	v_max3_f32 v140, v140, v86, v87
	v_max3_f32 v140, v140, v88, v89
	v_max3_f32 v140, v140, v90, v91
	v_max3_f32 v140, v140, v92, v93
	v_mfma_f32_32x32x16_bf16 v[4:19], v[144:147], v[192:195], v[4:19]
	v_max3_f32 v140, v140, v94, v95
	v_max3_f32 v140, v140, v96, v97
	v_max3_f32 v140, v140, v98, v99
	v_max3_f32 v140, v140, v68, v69
	v_max3_f32 v140, v140, v70, v71
	v_max3_f32 v140, v140, v72, v73
	v_max3_f32 v140, v140, v74, v75
	v_mfma_f32_32x32x16_bf16 v[4:19], v[148:151], v[196:199], v[4:19]
	v_max3_f32 v140, v140, v76, v77
	v_max3_f32 v140, v140, v78, v79
	v_max3_f32 v140, v140, v80, v81
	v_max3_f32 v140, v140, v82, v83
	v_mov_b32_e32 v141, v140
	s_nop 1
	v_permlane32_swap_b32_e32 v140, v141
	v_mfma_f32_32x32x16_bf16 v[4:19], v[152:155], v[200:203], v[4:19]
	v_max_f32_e32 v141, v141, v141
	v_max_f32_e32 v140, v140, v140
	v_max_f32_e32 v140, v140, v141
	v_sub_f32_e32 v141, v140, v185
	v_cmp_ge_f32_e32 vcc, s58, v141
	s_waitcnt lgkmcnt(0)
	s_barrier
	s_waitcnt vmcnt(0)
	s_cmp_eq_u64 vcc, exec
	s_cselect_b64 s[14:15], -1, 0
	s_waitcnt vmcnt(0)
	ds_write_b128 v179, v[212:215]
	ds_write_b128 v180, v[216:219]
	ds_write_b128 v183, v[220:223] offset:32768
	s_and_saveexec_b64 s[42:43], s[12:13]
	ds_write_b128 v186, v[224:227] offset:32768
	s_or_b64 exec, exec, s[42:43]
	v_max_f32_e32 v128, v185, v185
	v_max_f32_e32 v128, v128, v140
	v_sub_f32_e32 v129, v185, v128
	v_mul_f32_e32 v129, 0x3dd53b94, v129
	v_exp_f32_e32 v129, v129
	s_nop 0
	v_cndmask_b32_e64 v188, v129, 1.0, s[14:15]
	v_cmp_gt_f32_e32 vcc, 1.0, v188
	s_cbranch_vccz .LBB0_2422
	s_and_saveexec_b64 s[42:43], s[10:11]
	ds_write_b32 v175, v188 offset:57472
	s_or_b64 exec, exec, s[42:43]
	s_waitcnt lgkmcnt(0)
	v_add_u32_e32 v129, v157, v174
	ds_read_b128 v[130:133], v129 offset:57568
	ds_read_b128 v[134:137], v129 offset:57536
	ds_read_b128 v[138:141], v129 offset:57504
	ds_read_b128 v[142:145], v129 offset:57472
	s_waitcnt lgkmcnt(3)
	v_pk_mul_f32 v[64:65], v[64:65], v[130:131]
	s_waitcnt lgkmcnt(2)
	v_pk_mul_f32 v[60:61], v[60:61], v[134:135]
	s_waitcnt lgkmcnt(1)
	v_pk_mul_f32 v[56:57], v[56:57], v[138:139]
	v_pk_mul_f32 v[66:67], v[66:67], v[132:133]
	v_pk_mul_f32 v[62:63], v[62:63], v[136:137]
	v_pk_mul_f32 v[58:59], v[58:59], v[140:141]
	s_waitcnt lgkmcnt(0)
	v_pk_mul_f32 v[54:55], v[54:55], v[144:145]
	v_pk_mul_f32 v[52:53], v[52:53], v[142:143]
	v_pk_mul_f32 v[48:49], v[48:49], v[130:131]
	v_pk_mul_f32 v[44:45], v[44:45], v[134:135]
	v_pk_mul_f32 v[40:41], v[40:41], v[138:139]
	v_pk_mul_f32 v[50:51], v[50:51], v[132:133]
	v_pk_mul_f32 v[46:47], v[46:47], v[136:137]
	v_pk_mul_f32 v[42:43], v[42:43], v[140:141]
	v_pk_mul_f32 v[38:39], v[38:39], v[144:145]
	v_pk_mul_f32 v[36:37], v[36:37], v[142:143]
	v_pk_mul_f32 v[32:33], v[32:33], v[130:131]
	v_pk_mul_f32 v[28:29], v[28:29], v[134:135]
	v_pk_mul_f32 v[24:25], v[24:25], v[138:139]
	v_pk_mul_f32 v[34:35], v[34:35], v[132:133]
	v_pk_mul_f32 v[30:31], v[30:31], v[136:137]
	v_pk_mul_f32 v[26:27], v[26:27], v[140:141]
	v_pk_mul_f32 v[22:23], v[22:23], v[144:145]
	v_pk_mul_f32 v[20:21], v[20:21], v[142:143]
	v_pk_mul_f32 v[16:17], v[16:17], v[130:131]
	v_pk_mul_f32 v[12:13], v[12:13], v[134:135]
	v_pk_mul_f32 v[8:9], v[8:9], v[138:139]
	v_pk_mul_f32 v[18:19], v[18:19], v[132:133]
	v_pk_mul_f32 v[14:15], v[14:15], v[136:137]
	v_pk_mul_f32 v[10:11], v[10:11], v[140:141]
	v_pk_mul_f32 v[6:7], v[6:7], v[144:145]
	v_pk_mul_f32 v[4:5], v[4:5], v[142:143]
.LBB0_2422:
	v_cndmask_b32_e64 v185, v128, v185, s[14:15]
	v_mul_f32_e32 v138, 0xbdd53b94, v185
	v_fmamk_f32 v84, v84, 0x3dd53b94, v138
	v_fmamk_f32 v85, v85, 0x3dd53b94, v138
	v_fmamk_f32 v86, v86, 0x3dd53b94, v138
	v_fmamk_f32 v87, v87, 0x3dd53b94, v138
	v_fmamk_f32 v88, v88, 0x3dd53b94, v138
	v_fmamk_f32 v89, v89, 0x3dd53b94, v138
	v_fmamk_f32 v90, v90, 0x3dd53b94, v138
	v_fmamk_f32 v91, v91, 0x3dd53b94, v138
	v_fmamk_f32 v92, v92, 0x3dd53b94, v138
	v_fmamk_f32 v93, v93, 0x3dd53b94, v138
	v_fmamk_f32 v94, v94, 0x3dd53b94, v138
	v_fmamk_f32 v95, v95, 0x3dd53b94, v138
	v_fmamk_f32 v96, v96, 0x3dd53b94, v138
	v_fmamk_f32 v97, v97, 0x3dd53b94, v138
	v_fmamk_f32 v98, v98, 0x3dd53b94, v138
	v_fmamk_f32 v99, v99, 0x3dd53b94, v138
	v_exp_f32_e32 v131, v84
	v_exp_f32_e32 v134, v85
	v_exp_f32_e32 v135, v86
	v_exp_f32_e32 v139, v87
	v_exp_f32_e32 v142, v88
	v_exp_f32_e32 v143, v89
	v_exp_f32_e32 v144, v90
	v_exp_f32_e32 v145, v91
	v_exp_f32_e32 v128, v92
	v_exp_f32_e32 v129, v93
	v_exp_f32_e32 v130, v94
	v_exp_f32_e32 v132, v95
	v_exp_f32_e32 v133, v96
	v_exp_f32_e32 v136, v97
	v_exp_f32_e32 v137, v98
	v_exp_f32_e32 v147, v99
	v_fmamk_f32 v140, v68, 0x3dd53b94, v138
	v_fmamk_f32 v141, v69, 0x3dd53b94, v138
	v_fmamk_f32 v146, v70, 0x3dd53b94, v138
	v_fmamk_f32 v148, v71, 0x3dd53b94, v138
	v_fmamk_f32 v149, v72, 0x3dd53b94, v138
	v_fmamk_f32 v150, v73, 0x3dd53b94, v138
	v_fmamk_f32 v151, v74, 0x3dd53b94, v138
	v_fmamk_f32 v152, v75, 0x3dd53b94, v138
	v_fmamk_f32 v153, v76, 0x3dd53b94, v138
	v_fmamk_f32 v154, v77, 0x3dd53b94, v138
	v_fmamk_f32 v155, v78, 0x3dd53b94, v138
	v_fmamk_f32 v189, v79, 0x3dd53b94, v138
	v_fmamk_f32 v190, v80, 0x3dd53b94, v138
	v_fmamk_f32 v191, v81, 0x3dd53b94, v138
	v_fmamk_f32 v192, v82, 0x3dd53b94, v138
	v_fmac_f32_e32 v138, 0x3dd53b94, v83
	s_waitcnt lgkmcnt(0)
	s_barrier
	s_mov_b64 s[100:101], 0x2a10c000
	v_lshl_add_u64 v[212:213], v[228:229], 0, s[100:101]
	s_mov_b64 s[100:101], 0x2a10e000
	v_lshl_add_u64 v[216:217], v[228:229], 0, s[100:101]
	s_mov_b64 s[100:101], 0x1e109000
	v_lshl_add_u64 v[220:221], v[230:231], 0, s[100:101]
	v_lshl_add_u64 v[224:225], v[232:233], 0, s[100:101]
	global_load_dwordx4 v[212:215], v[212:213], off
	global_load_dwordx4 v[216:219], v[216:217], off
	global_load_dwordx4 v[220:223], v[220:221], off
	s_and_saveexec_b64 s[14:15], s[12:13]
	s_cbranch_execz .Lattn_ldB_skip
	global_load_dwordx4 v[224:227], v[224:225], off
.Lattn_ldB_skip:
	s_or_b64 exec, exec, s[14:15]
	s_nop 1
	ds_read_b128 v[194:197], v181
	ds_read_b128 v[202:205], v181 offset:6144
	ds_read_b128 v[198:201], v182
	ds_read_b128 v[206:209], v182 offset:6144
	v_exp_f32_e32 v193, v140
	v_add_f32_e32 v140, 0, v131
	v_mov_b64_e32 v[82:83], s[30:31]
	v_add_f32_e32 v140, v134, v140
	v_mov_b64_e32 v[80:81], s[28:29]
	v_mov_b64_e32 v[78:79], s[26:27]
	v_mov_b64_e32 v[76:77], s[24:25]
	v_mov_b64_e32 v[74:75], s[22:23]
	v_mov_b64_e32 v[72:73], s[20:21]
	v_mov_b64_e32 v[70:71], s[18:19]
	v_mov_b64_e32 v[68:69], s[16:17]
	v_mov_b64_e32 v[98:99], v[82:83]
	v_add_f32_e32 v140, v135, v140
	v_mov_b64_e32 v[96:97], v[80:81]
	v_mov_b64_e32 v[94:95], v[78:79]
	v_mov_b64_e32 v[92:93], v[76:77]
	v_mov_b64_e32 v[90:91], v[74:75]
	v_mov_b64_e32 v[88:89], v[72:73]
	v_mov_b64_e32 v[86:87], v[70:71]
	v_mov_b64_e32 v[84:85], v[68:69]
	v_add_f32_e32 v140, v139, v140
	s_waitcnt lgkmcnt(1)
	v_mfma_scale_f32_32x32x64_f8f6f4 v[84:99], v[194:201], v[116:123], v[84:99], v170, v170 op_sel_hi:[0,0,0]
	s_waitcnt lgkmcnt(0)
	v_mfma_scale_f32_32x32x64_f8f6f4 v[68:83], v[202:209], v[116:123], v[68:83], v170, v170 op_sel_hi:[0,0,0]
	ds_read_b128 v[194:197], v181 offset:64
	ds_read_b128 v[202:205], v181 offset:6208
	ds_read_b128 v[198:201], v182 offset:64
	ds_read_b128 v[206:209], v182 offset:6208
	v_add_f32_e32 v140, v142, v140
	v_add_f32_e32 v140, v143, v140
	v_add_f32_e32 v140, v144, v140
	v_add_f32_e32 v140, v145, v140
	v_add_f32_e32 v140, v128, v140
	s_waitcnt lgkmcnt(1)
	v_mfma_scale_f32_32x32x64_f8f6f4 v[84:99], v[194:201], v[108:115], v[84:99], v170, v170 op_sel_hi:[0,0,0]
	s_waitcnt lgkmcnt(0)
	v_mfma_scale_f32_32x32x64_f8f6f4 v[68:83], v[202:209], v[108:115], v[68:83], v170, v170 op_sel_hi:[0,0,0]
	ds_read_b128 v[194:197], v181 offset:128
	ds_read_b128 v[202:205], v181 offset:6272
	ds_read_b128 v[198:201], v182 offset:128
	ds_read_b128 v[206:209], v182 offset:6272
	v_add_f32_e32 v140, v129, v140
	v_add_f32_e32 v140, v130, v140
	v_add_f32_e32 v140, v132, v140
	v_add_f32_e32 v140, v133, v140
	s_waitcnt lgkmcnt(1)
	v_mfma_scale_f32_32x32x64_f8f6f4 v[84:99], v[194:201], v[100:107], v[84:99], v170, v170 op_sel_hi:[0,0,0]
	v_exp_f32_e32 v194, v141
	v_add_f32_e32 v140, v136, v140
	v_exp_f32_e32 v195, v146
	v_add_f32_e32 v140, v137, v140
	v_exp_f32_e32 v196, v148
	v_add_f32_e32 v140, v147, v140
	v_exp_f32_e32 v197, v149
	v_add_f32_e32 v140, v193, v140
	v_exp_f32_e32 v150, v150
	v_add_f32_e32 v140, v194, v140
	v_exp_f32_e32 v151, v151
	v_add_f32_e32 v140, v195, v140
	v_exp_f32_e32 v152, v152
	v_add_f32_e32 v140, v196, v140
	v_exp_f32_e32 v153, v153
	v_add_f32_e32 v140, v197, v140
	v_exp_f32_e32 v154, v154
	v_add_f32_e32 v140, v150, v140
	v_exp_f32_e32 v155, v155
	v_add_f32_e32 v140, v151, v140
	v_exp_f32_e32 v198, v189
	v_add_f32_e32 v140, v152, v140
	v_exp_f32_e32 v199, v190
	v_add_f32_e32 v140, v153, v140
	v_exp_f32_e32 v191, v191
	v_add_f32_e32 v140, v154, v140
	v_exp_f32_e32 v192, v192
	v_add_f32_e32 v140, v155, v140
	v_exp_f32_e32 v138, v138
	v_add_f32_e32 v140, v198, v140
	v_add_f32_e32 v140, v199, v140
	v_add_f32_e32 v140, v191, v140
	v_add_f32_e32 v140, v192, v140
	v_add_f32_e32 v189, v138, v140
	v_mov_b32_e32 v190, v189
	v_cvt_pk_bf16_f32 v140, v131, v134
	v_cvt_pk_bf16_f32 v141, v135, v139
	v_cvt_pk_bf16_f32 v142, v142, v143
	v_cvt_pk_bf16_f32 v143, v144, v145
	v_cvt_pk_bf16_f32 v144, v128, v129
	v_cvt_pk_bf16_f32 v145, v130, v132
	v_cvt_pk_bf16_f32 v146, v133, v136
	v_cvt_pk_bf16_f32 v147, v137, v147
	v_cvt_pk_bf16_f32 v148, v193, v194
	v_cvt_pk_bf16_f32 v149, v195, v196
	v_cvt_pk_bf16_f32 v150, v197, v150
	v_cvt_pk_bf16_f32 v151, v151, v152
	v_cvt_pk_bf16_f32 v152, v153, v154
	v_cvt_pk_bf16_f32 v153, v155, v198
	v_cvt_pk_bf16_f32 v154, v199, v191
	v_cvt_pk_bf16_f32 v155, v192, v138
	s_waitcnt lgkmcnt(0)
	v_mfma_scale_f32_32x32x64_f8f6f4 v[68:83], v[202:209], v[100:107], v[68:83], v170, v170 op_sel_hi:[0,0,0]
	v_permlane32_swap_b32_e32 v189, v190
	v_permlane32_swap_b32_e32 v140, v142
	v_permlane32_swap_b32_e32 v141, v143
	v_permlane32_swap_b32_e32 v144, v146
	v_permlane32_swap_b32_e32 v145, v147
	v_permlane32_swap_b32_e32 v148, v150
	v_permlane32_swap_b32_e32 v149, v151
	v_permlane32_swap_b32_e32 v152, v154
	v_permlane32_swap_b32_e32 v153, v155
	ds_read_b64_tr_b16 v[164:165], v176 offset:0
	ds_read_b64_tr_b16 v[166:167], v176 offset:0x800
	ds_read_b64_tr_b16 v[192:193], v176 offset:0x1000
	ds_read_b64_tr_b16 v[194:195], v176 offset:0x1800
	ds_read_b64_tr_b16 v[196:197], v176 offset:0x2000
	ds_read_b64_tr_b16 v[198:199], v176 offset:0x2800
	ds_read_b64_tr_b16 v[200:201], v176 offset:0x3000
	ds_read_b64_tr_b16 v[202:203], v176 offset:0x3800
	s_waitcnt lgkmcnt(0)
	s_nop 0
	v_mfma_f32_32x32x16_bf16 v[52:67], v[140:143], v[164:167], v[52:67]
	ds_read_b64_tr_b16 v[164:165], v176 offset:0x200
	ds_read_b64_tr_b16 v[166:167], v176 offset:0xa00
	v_mfma_f32_32x32x16_bf16 v[52:67], v[144:147], v[192:195], v[52:67]
	ds_read_b64_tr_b16 v[192:193], v176 offset:0x1200
	ds_read_b64_tr_b16 v[194:195], v176 offset:0x1a00
	v_mfma_f32_32x32x16_bf16 v[52:67], v[148:151], v[196:199], v[52:67]
	ds_read_b64_tr_b16 v[196:197], v176 offset:0x2200
	ds_read_b64_tr_b16 v[198:199], v176 offset:0x2a00
	v_mfma_f32_32x32x16_bf16 v[52:67], v[152:155], v[200:203], v[52:67]
	ds_read_b64_tr_b16 v[200:201], v176 offset:0x3200
	ds_read_b64_tr_b16 v[202:203], v176 offset:0x3a00
	s_waitcnt lgkmcnt(0)
	v_mfma_f32_32x32x16_bf16 v[36:51], v[140:143], v[164:167], v[36:51]
	ds_read_b64_tr_b16 v[164:165], v176 offset:0x400
	ds_read_b64_tr_b16 v[166:167], v176 offset:0xc00
	v_mfma_f32_32x32x16_bf16 v[36:51], v[144:147], v[192:195], v[36:51]
	ds_read_b64_tr_b16 v[192:193], v176 offset:0x1400
	ds_read_b64_tr_b16 v[194:195], v176 offset:0x1c00
	v_mfma_f32_32x32x16_bf16 v[36:51], v[148:151], v[196:199], v[36:51]
	ds_read_b64_tr_b16 v[196:197], v176 offset:0x2400
	ds_read_b64_tr_b16 v[198:199], v176 offset:0x2c00
	v_mfma_f32_32x32x16_bf16 v[36:51], v[152:155], v[200:203], v[36:51]
	ds_read_b64_tr_b16 v[200:201], v176 offset:0x3400
	ds_read_b64_tr_b16 v[202:203], v176 offset:0x3c00
	s_waitcnt lgkmcnt(0)
	v_mfma_f32_32x32x16_bf16 v[20:35], v[140:143], v[164:167], v[20:35]
	ds_read_b64_tr_b16 v[164:165], v176 offset:0x600
	ds_read_b64_tr_b16 v[166:167], v176 offset:0xe00
	v_mfma_f32_32x32x16_bf16 v[20:35], v[144:147], v[192:195], v[20:35]
	ds_read_b64_tr_b16 v[192:193], v176 offset:0x1600
	ds_read_b64_tr_b16 v[194:195], v176 offset:0x1e00
	v_mfma_f32_32x32x16_bf16 v[20:35], v[148:151], v[196:199], v[20:35]
	ds_read_b64_tr_b16 v[196:197], v176 offset:0x2600
	ds_read_b64_tr_b16 v[198:199], v176 offset:0x2e00
	v_mfma_f32_32x32x16_bf16 v[20:35], v[152:155], v[200:203], v[20:35]
	ds_read_b64_tr_b16 v[200:201], v176 offset:0x3600
	ds_read_b64_tr_b16 v[202:203], v176 offset:0x3e00
	s_waitcnt lgkmcnt(0)
	v_mfma_f32_32x32x16_bf16 v[4:19], v[140:143], v[164:167], v[4:19]
	v_max_f32_e32 v140, v85, v85
	v_max_f32_e32 v141, v84, v84
	v_max_f32_e32 v140, v141, v140
	v_max3_f32 v140, v140, v86, v87
	v_max3_f32 v140, v140, v88, v89
	v_max3_f32 v140, v140, v90, v91
	v_max3_f32 v140, v140, v92, v93
	v_mfma_f32_32x32x16_bf16 v[4:19], v[144:147], v[192:195], v[4:19]
	v_max3_f32 v140, v140, v94, v95
	v_max3_f32 v140, v140, v96, v97
	v_max3_f32 v140, v140, v98, v99
	v_max3_f32 v140, v140, v68, v69
	v_max3_f32 v140, v140, v70, v71
	v_max3_f32 v140, v140, v72, v73
	v_max3_f32 v140, v140, v74, v75
	v_mfma_f32_32x32x16_bf16 v[4:19], v[148:151], v[196:199], v[4:19]
	v_max3_f32 v140, v140, v76, v77
	v_max3_f32 v140, v140, v78, v79
	v_max3_f32 v140, v140, v80, v81
	v_max3_f32 v140, v140, v82, v83
	v_mov_b32_e32 v141, v140
	s_nop 1
	v_permlane32_swap_b32_e32 v140, v141
	v_mfma_f32_32x32x16_bf16 v[4:19], v[152:155], v[200:203], v[4:19]
	v_max_f32_e32 v141, v141, v141
	v_max_f32_e32 v140, v140, v140
	v_max_f32_e32 v140, v140, v141
	v_sub_f32_e32 v141, v140, v185
	v_cmp_ge_f32_e32 vcc, s58, v141
	s_waitcnt lgkmcnt(0)
	s_barrier
	s_waitcnt vmcnt(0)
	s_cmp_eq_u64 vcc, exec
	s_cselect_b64 s[14:15], -1, 0
	s_waitcnt vmcnt(0)
	ds_write_b128 v179, v[212:215] offset:16384
	ds_write_b128 v180, v[216:219] offset:16384
	ds_write_b128 v183, v[220:223] offset:45056
	s_and_saveexec_b64 s[42:43], s[12:13]
	ds_write_b128 v186, v[224:227] offset:45056
	s_or_b64 exec, exec, s[42:43]
	v_max_f32_e32 v128, v185, v185
	v_max_f32_e32 v128, v128, v140
	v_sub_f32_e32 v129, v185, v128
	v_mul_f32_e32 v129, 0x3dd53b94, v129
	v_exp_f32_e32 v129, v129
	s_nop 0
	v_cndmask_b32_e64 v144, v129, 1.0, s[14:15]
	v_cmp_gt_f32_e32 vcc, 1.0, v144
	s_cbranch_vccz .LBB0_2430
	s_and_saveexec_b64 s[42:43], s[10:11]
	ds_write_b32 v175, v144 offset:57472
	s_or_b64 exec, exec, s[42:43]
	s_waitcnt lgkmcnt(0)
	v_add_u32_e32 v129, v157, v174
	ds_read_b128 v[130:133], v129 offset:57568
	ds_read_b128 v[134:137], v129 offset:57536
	ds_read_b128 v[138:141], v129 offset:57504
	ds_read_b128 v[146:149], v129 offset:57472
	s_waitcnt lgkmcnt(3)
	v_pk_mul_f32 v[64:65], v[64:65], v[130:131]
	s_waitcnt lgkmcnt(2)
	v_pk_mul_f32 v[60:61], v[60:61], v[134:135]
	s_waitcnt lgkmcnt(1)
	v_pk_mul_f32 v[56:57], v[56:57], v[138:139]
	v_pk_mul_f32 v[66:67], v[66:67], v[132:133]
	v_pk_mul_f32 v[62:63], v[62:63], v[136:137]
	v_pk_mul_f32 v[58:59], v[58:59], v[140:141]
	s_waitcnt lgkmcnt(0)
	v_pk_mul_f32 v[54:55], v[54:55], v[148:149]
	v_pk_mul_f32 v[52:53], v[52:53], v[146:147]
	v_pk_mul_f32 v[48:49], v[48:49], v[130:131]
	v_pk_mul_f32 v[44:45], v[44:45], v[134:135]
	v_pk_mul_f32 v[40:41], v[40:41], v[138:139]
	v_pk_mul_f32 v[50:51], v[50:51], v[132:133]
	v_pk_mul_f32 v[46:47], v[46:47], v[136:137]
	v_pk_mul_f32 v[42:43], v[42:43], v[140:141]
	v_pk_mul_f32 v[38:39], v[38:39], v[148:149]
	v_pk_mul_f32 v[36:37], v[36:37], v[146:147]
	v_pk_mul_f32 v[32:33], v[32:33], v[130:131]
	v_pk_mul_f32 v[28:29], v[28:29], v[134:135]
	v_pk_mul_f32 v[24:25], v[24:25], v[138:139]
	v_pk_mul_f32 v[34:35], v[34:35], v[132:133]
	v_pk_mul_f32 v[30:31], v[30:31], v[136:137]
	v_pk_mul_f32 v[26:27], v[26:27], v[140:141]
	v_pk_mul_f32 v[22:23], v[22:23], v[148:149]
	v_pk_mul_f32 v[20:21], v[20:21], v[146:147]
	v_pk_mul_f32 v[16:17], v[16:17], v[130:131]
	v_pk_mul_f32 v[12:13], v[12:13], v[134:135]
	v_pk_mul_f32 v[8:9], v[8:9], v[138:139]
	v_pk_mul_f32 v[18:19], v[18:19], v[132:133]
	v_pk_mul_f32 v[14:15], v[14:15], v[136:137]
	v_pk_mul_f32 v[10:11], v[10:11], v[140:141]
	v_pk_mul_f32 v[6:7], v[6:7], v[148:149]
	v_pk_mul_f32 v[4:5], v[4:5], v[146:147]
